# tail split-K tiles: load->wait->MFMA chains pipelined over four register sets with counted waits
# baseline (speedup 1.0000x reference)
; #define MFMA32T(a, b, c) __builtin_amdgcn_mfma_f32_32x32x16_bf16((a), (b), (c), 0, 0, 0)
;     ...
;     for (int t = b0; t < mt * nt; t += G) { const int mb = t / nt, nb = t % nt;
;         const bf16_t* ap = A + (size_t)(mb * 32 + r) * lda + wave * 16 + 8 * hh; const int brow = f.brow(nb);
;         const bf16_t* bp = Bt + (size_t)(brow + r) * ldb + wave * 16 + 8 * hh; const bf16_t* bp2 = DUAL ? Bt2 + (size_t)(brow + r) * ldb + wave * 16 + 8 * hh : bp;
;         f32x16 acc, acc2;
; #pragma unroll
;         for (int i = 0; i < 16; ++i) { acc[i] = 0.f; acc2[i] = 0.f; }
; #pragma unroll 8
;         for (int k = 0; k < K; k += 128) { const bf16x8 av = *(const bf16x8*)(ap + k); acc = MFMA32T(av, *(const bf16x8*)(bp + k), acc); if (DUAL) acc2 = MFMA32T(av, *(const bf16x8*)(bp2 + k), acc2); }
; #pragma unroll
;         for (int i = 0; i < 16; ++i) { red[(wave * 16 + i) * 64 + lane] = acc[i]; if (DUAL) red[8192 + (wave * 16 + i) * 64 + lane] = acc2[i]; }
;         __syncthreads();
.LBB0_32:
	s_ashr_i32 s2, s0, 31
	s_lshr_b32 s2, s2, 27
	s_add_i32 s3, s0, s2
	s_ashr_i32 s23, s3, 5
	s_andn2_b32 s3, s3, 31
	s_lshl_b32 s2, s23, 10
	s_mul_i32 s23, s23, 0xffd40000
	v_or_b32_e32 v2, s3, v22
	v_add_u32_e32 v0, s23, v25
	v_ashrrev_i32_e32 v1, 31, v0
	v_mad_i64_i32 v[34:35], s[24:25], v2, s73, v[16:17]
	v_lshl_add_u64 v[36:37], v[0:1], 1, v[18:19]
	global_load_dwordx4 v[0:3], v[34:35], off
	global_load_dwordx4 v[4:7], v[36:37], off
	global_load_dwordx4 v[26:29], v[34:35], off offset:256
	global_load_dwordx4 v[30:33], v[36:37], off offset:256
	s_sub_i32 s2, s21, s2
	s_add_i32 s21, s21, s22
	s_waitcnt vmcnt(0)
	v_mfma_f32_32x32x16_bf16 v[0:15], v[0:3], v[4:7], 0
	s_waitcnt vmcnt(0)
	v_mfma_f32_32x32x16_bf16 v[0:15], v[26:29], v[30:33], v[0:15]
	global_load_dwordx4 v[26:29], v[34:35], off offset:512
	global_load_dwordx4 v[30:33], v[36:37], off offset:512
	global_load_dwordx4 v[200:203], v[34:35], off offset:768
	global_load_dwordx4 v[204:207], v[36:37], off offset:768
	global_load_dwordx4 v[212:215], v[34:35], off offset:1024
	global_load_dwordx4 v[216:219], v[36:37], off offset:1024
	global_load_dwordx4 v[224:227], v[34:35], off offset:1280
	global_load_dwordx4 v[228:231], v[36:37], off offset:1280
	s_waitcnt vmcnt(6)
	v_mfma_f32_32x32x16_bf16 v[0:15], v[26:29], v[30:33], v[0:15]
	global_load_dwordx4 v[26:29], v[34:35], off offset:1536
	global_load_dwordx4 v[30:33], v[36:37], off offset:1536
	s_waitcnt vmcnt(6)
	v_mfma_f32_32x32x16_bf16 v[0:15], v[200:203], v[204:207], v[0:15]
	global_load_dwordx4 v[200:203], v[34:35], off offset:1792
	global_load_dwordx4 v[204:207], v[36:37], off offset:1792
	s_waitcnt vmcnt(6)
	v_mfma_f32_32x32x16_bf16 v[0:15], v[212:215], v[216:219], v[0:15]
	global_load_dwordx4 v[212:215], v[34:35], off offset:2048
	global_load_dwordx4 v[216:219], v[36:37], off offset:2048
	s_waitcnt vmcnt(6)
	v_mfma_f32_32x32x16_bf16 v[0:15], v[224:227], v[228:231], v[0:15]
	global_load_dwordx4 v[224:227], v[34:35], off offset:2304
	global_load_dwordx4 v[228:231], v[36:37], off offset:2304
	s_waitcnt vmcnt(6)
	v_mfma_f32_32x32x16_bf16 v[0:15], v[26:29], v[30:33], v[0:15]
	global_load_dwordx4 v[26:29], v[34:35], off offset:2560
	global_load_dwordx4 v[30:33], v[36:37], off offset:2560
	s_waitcnt vmcnt(6)
	v_mfma_f32_32x32x16_bf16 v[0:15], v[200:203], v[204:207], v[0:15]
	global_load_dwordx4 v[200:203], v[34:35], off offset:2816
	global_load_dwordx4 v[204:207], v[36:37], off offset:2816
	s_waitcnt vmcnt(6)
	v_mfma_f32_32x32x16_bf16 v[0:15], v[212:215], v[216:219], v[0:15]
	global_load_dwordx4 v[212:215], v[34:35], off offset:3072
	global_load_dwordx4 v[216:219], v[36:37], off offset:3072
	s_waitcnt vmcnt(6)
	v_mfma_f32_32x32x16_bf16 v[0:15], v[224:227], v[228:231], v[0:15]
	global_load_dwordx4 v[224:227], v[34:35], off offset:3328
	global_load_dwordx4 v[228:231], v[36:37], off offset:3328
	s_waitcnt vmcnt(6)
	v_mfma_f32_32x32x16_bf16 v[0:15], v[26:29], v[30:33], v[0:15]
	global_load_dwordx4 v[26:29], v[34:35], off offset:3584
	global_load_dwordx4 v[30:33], v[36:37], off offset:3584
	s_waitcnt vmcnt(6)
	v_mfma_f32_32x32x16_bf16 v[0:15], v[200:203], v[204:207], v[0:15]
	s_waitcnt vmcnt(4)
	v_mfma_f32_32x32x16_bf16 v[0:15], v[212:215], v[216:219], v[0:15]
	s_waitcnt vmcnt(2)
	v_mfma_f32_32x32x16_bf16 v[0:15], v[224:227], v[228:231], v[0:15]
	s_waitcnt vmcnt(0)
	v_mfma_f32_32x32x16_bf16 v[0:15], v[26:29], v[30:33], v[0:15]
	global_load_dwordx4 v[26:29], v[34:35], off offset:3840
	global_load_dwordx4 v[30:33], v[36:37], off offset:3840
	v_add_co_u32_e32 v34, vcc, s74, v34
	s_nop 1
	v_addc_co_u32_e32 v35, vcc, 0, v35, vcc
	v_add_co_u32_e32 v36, vcc, s74, v36
	s_waitcnt vmcnt(0)
	v_mfma_f32_32x32x16_bf16 v[0:15], v[26:29], v[30:33], v[0:15]
	global_load_dwordx4 v[26:29], v[34:35], off
	v_addc_co_u32_e32 v37, vcc, 0, v37, vcc
	global_load_dwordx4 v[30:33], v[36:37], off
	s_waitcnt vmcnt(0)
	v_mfma_f32_32x32x16_bf16 v[0:15], v[26:29], v[30:33], v[0:15]
	global_load_dwordx4 v[26:29], v[34:35], off offset:256
	global_load_dwordx4 v[30:33], v[36:37], off offset:256
	global_load_dwordx4 v[200:203], v[34:35], off offset:512
	global_load_dwordx4 v[204:207], v[36:37], off offset:512
	global_load_dwordx4 v[212:215], v[34:35], off offset:768
	global_load_dwordx4 v[216:219], v[36:37], off offset:768
	global_load_dwordx4 v[224:227], v[34:35], off offset:1024
	global_load_dwordx4 v[228:231], v[36:37], off offset:1024
	s_waitcnt vmcnt(6)
	v_mfma_f32_32x32x16_bf16 v[0:15], v[26:29], v[30:33], v[0:15]
	global_load_dwordx4 v[26:29], v[34:35], off offset:1280
	global_load_dwordx4 v[30:33], v[36:37], off offset:1280
	s_waitcnt vmcnt(6)
	v_mfma_f32_32x32x16_bf16 v[0:15], v[200:203], v[204:207], v[0:15]
	s_waitcnt vmcnt(4)
	v_mfma_f32_32x32x16_bf16 v[0:15], v[212:215], v[216:219], v[0:15]
	s_waitcnt vmcnt(2)
	v_mfma_f32_32x32x16_bf16 v[0:15], v[224:227], v[228:231], v[0:15]
	s_waitcnt vmcnt(0)
	v_mfma_f32_32x32x16_bf16 v[0:15], v[26:29], v[30:33], v[0:15]
	v_add_u32_e32 v26, s1, v23
	s_nop 10
	ds_write2st64_b32 v26, v0, v1 offset1:1
	ds_write2st64_b32 v26, v2, v3 offset0:2 offset1:3
	ds_write2st64_b32 v26, v4, v5 offset0:4 offset1:5
	ds_write2st64_b32 v26, v6, v7 offset0:6 offset1:7
	ds_write2st64_b32 v26, v8, v9 offset0:8 offset1:9
	ds_write2st64_b32 v26, v10, v11 offset0:10 offset1:11
	ds_write2st64_b32 v26, v12, v13 offset0:12 offset1:13
	ds_write2st64_b32 v26, v14, v15 offset0:14 offset1:15
	v_add_u32_e32 v5, s4, v23
	s_waitcnt lgkmcnt(0)
	s_barrier
; __device__ __forceinline__ int crow32(int i, int hh) { return (i & 3) + 8 * (i >> 2) + 4 * hh; }
;     ...
;         for (int ii = 0; ii < 2; ++ii) { const int i = 2 * wave + ii; float v = 0.f, v2 = 0.f;
; #pragma unroll
;             for (int w = 0; w < 8; ++w) { v += red[(w * 16 + i) * 64 + lane]; if (DUAL) v2 += red[8192 + (w * 16 + i) * 64 + lane]; }
;             f(v, v2, mb * 32 + crow32(i, hh), nb * 32, r); }
;         __syncthreads();
	ds_read2st64_b32 v[2:3], v5 offset1:16
	v_or_b32_e32 v4, s3, v24
	s_ashr_i32 s3, s2, 31
	v_lshl_add_u64 v[0:1], s[2:3], 1, v[20:21]
	s_mul_i32 s2, s83, 0x16000
	s_waitcnt lgkmcnt(0)
	v_add_f32_e32 v2, 0, v2
	v_add_f32_e32 v6, v2, v3
	ds_read2st64_b32 v[2:3], v5 offset0:32 offset1:48
	v_add_u32_e32 v25, s2, v25
	s_waitcnt lgkmcnt(0)
	v_add_f32_e32 v2, v6, v2
	v_add_f32_e32 v6, v2, v3
	ds_read2st64_b32 v[2:3], v5 offset0:64 offset1:80
	s_waitcnt lgkmcnt(0)
	v_add_f32_e32 v2, v6, v2
	v_add_f32_e32 v6, v2, v3
	ds_read2st64_b32 v[2:3], v5 offset0:96 offset1:112
	s_waitcnt lgkmcnt(0)
	v_add_f32_e32 v2, v6, v2
	v_add_f32_e32 v3, v2, v3
	v_add_u32_e32 v2, s5, v4
	v_cvt_pk_bf16_f32 v5, v3, s0
	v_ashrrev_i32_e32 v3, 31, v2
	v_lshlrev_b64 v[2:3], 11, v[2:3]
	v_lshl_add_u64 v[2:3], v[0:1], 0, v[2:3]
	global_store_short v[2:3], v5, off
	v_add_u32_e32 v5, s12, v23
	ds_read2st64_b32 v[2:3], v5 offset1:16
	s_waitcnt lgkmcnt(0)
	v_add_f32_e32 v2, 0, v2
	v_add_f32_e32 v6, v2, v3
	ds_read2st64_b32 v[2:3], v5 offset0:32 offset1:48
	s_waitcnt lgkmcnt(0)
	v_add_f32_e32 v2, v6, v2
	v_add_f32_e32 v6, v2, v3
	ds_read2st64_b32 v[2:3], v5 offset0:64 offset1:80
	s_waitcnt lgkmcnt(0)
	v_add_f32_e32 v2, v6, v2
	v_add_f32_e32 v6, v2, v3
	ds_read2st64_b32 v[2:3], v5 offset0:96 offset1:112
	s_waitcnt lgkmcnt(0)
	v_add_f32_e32 v2, v6, v2
	v_add_f32_e32 v3, v2, v3
	v_add_u32_e32 v2, s20, v4
	v_cvt_pk_bf16_f32 v4, v3, s0
	v_ashrrev_i32_e32 v3, 31, v2
	v_lshlrev_b64 v[2:3], 11, v[2:3]
	s_add_i32 s0, s0, s83
	v_lshl_add_u64 v[0:1], v[0:1], 0, v[2:3]
	s_cmpk_gt_i32 s0, 0xff
	global_store_short v[0:1], v4, off
	s_barrier
	s_cbranch_scc0 .LBB0_32

; #define MFMA32T(a, b, c) __builtin_amdgcn_mfma_f32_32x32x16_bf16((a), (b), (c), 0, 0, 0)
;     ...
;     for (int t = b0; t < mt * nt; t += G) { const int mb = t / nt, nb = t % nt;
;         const bf16_t* ap = A + (size_t)(mb * 32 + r) * lda + wave * 16 + 8 * hh; const int brow = f.brow(nb);
;         const bf16_t* bp = Bt + (size_t)(brow + r) * ldb + wave * 16 + 8 * hh; const bf16_t* bp2 = DUAL ? Bt2 + (size_t)(brow + r) * ldb + wave * 16 + 8 * hh : bp;
;         f32x16 acc, acc2;
; #pragma unroll
;         for (int i = 0; i < 16; ++i) { acc[i] = 0.f; acc2[i] = 0.f; }
; #pragma unroll 8
;         for (int k = 0; k < K; k += 128) { const bf16x8 av = *(const bf16x8*)(ap + k); acc = MFMA32T(av, *(const bf16x8*)(bp + k), acc); if (DUAL) acc2 = MFMA32T(av, *(const bf16x8*)(bp2 + k), acc2); }
; #pragma unroll
;         for (int i = 0; i < 16; ++i) { red[(wave * 16 + i) * 64 + lane] = acc[i]; if (DUAL) red[8192 + (wave * 16 + i) * 64 + lane] = acc2[i]; }
;         __syncthreads();
.LBB0_101:
	s_ashr_i32 s20, s44, 31
	s_lshr_b32 s20, s20, 27
	s_add_i32 s20, s44, s20
	s_and_b32 s21, s20, 0xffffffe0
	s_lshl_b32 s20, s20, 5
	s_and_b32 s20, s20, 0xfffffc00
	v_or_b32_e32 v0, s21, v16
	s_sub_i32 s20, s41, s20
	v_ashrrev_i32_e32 v1, 31, v0
	v_add_u32_e32 v2, s20, v16
	v_ashrrev_i32_e32 v3, 31, v2
	v_lshlrev_b64 v[0:1], 11, v[0:1]
	v_lshl_add_u64 v[34:35], v[20:21], 0, v[0:1]
	v_lshlrev_b64 v[0:1], 11, v[2:3]
	v_lshl_add_u64 v[36:37], v[22:23], 0, v[0:1]
	global_load_dwordx4 v[0:3], v[34:35], off
	global_load_dwordx4 v[4:7], v[36:37], off
	global_load_dwordx4 v[26:29], v[34:35], off offset:256
	global_load_dwordx4 v[30:33], v[36:37], off offset:256
	s_add_i32 s44, s44, s83
	s_add_i32 s41, s41, s23
	s_waitcnt vmcnt(0)
	v_mfma_f32_32x32x16_bf16 v[0:15], v[0:3], v[4:7], 0
	s_waitcnt vmcnt(0)
	v_mfma_f32_32x32x16_bf16 v[0:15], v[26:29], v[30:33], v[0:15]
	global_load_dwordx4 v[26:29], v[34:35], off offset:512
	global_load_dwordx4 v[30:33], v[36:37], off offset:512
	global_load_dwordx4 v[200:203], v[34:35], off offset:768
	global_load_dwordx4 v[204:207], v[36:37], off offset:768
	global_load_dwordx4 v[212:215], v[34:35], off offset:1024
	global_load_dwordx4 v[216:219], v[36:37], off offset:1024
	global_load_dwordx4 v[224:227], v[34:35], off offset:1280
	global_load_dwordx4 v[228:231], v[36:37], off offset:1280
	s_waitcnt vmcnt(6)
	v_mfma_f32_32x32x16_bf16 v[0:15], v[26:29], v[30:33], v[0:15]
	global_load_dwordx4 v[26:29], v[34:35], off offset:1536
	global_load_dwordx4 v[30:33], v[36:37], off offset:1536
	s_waitcnt vmcnt(6)
	v_mfma_f32_32x32x16_bf16 v[0:15], v[200:203], v[204:207], v[0:15]
	global_load_dwordx4 v[200:203], v[34:35], off offset:1792
	global_load_dwordx4 v[204:207], v[36:37], off offset:1792
	s_waitcnt vmcnt(6)
	v_mfma_f32_32x32x16_bf16 v[0:15], v[212:215], v[216:219], v[0:15]
	s_waitcnt vmcnt(4)
	v_mfma_f32_32x32x16_bf16 v[0:15], v[224:227], v[228:231], v[0:15]
	s_waitcnt vmcnt(2)
	v_mfma_f32_32x32x16_bf16 v[0:15], v[26:29], v[30:33], v[0:15]
	s_waitcnt vmcnt(0)
	v_mfma_f32_32x32x16_bf16 v[0:15], v[200:203], v[204:207], v[0:15]
	v_add_u32_e32 v26, s29, v19
	v_add_u32_e32 v27, s33, v19
	s_nop 9
	ds_write2st64_b32 v26, v0, v1 offset1:1
	ds_write2st64_b32 v26, v2, v3 offset0:2 offset1:3
	ds_write2st64_b32 v26, v4, v5 offset0:4 offset1:5
	ds_write2st64_b32 v26, v6, v7 offset0:6 offset1:7
	ds_write2st64_b32 v26, v8, v9 offset0:8 offset1:9
	ds_write2st64_b32 v26, v10, v11 offset0:10 offset1:11
	ds_write2st64_b32 v26, v12, v13 offset0:12 offset1:13
	ds_write2st64_b32 v26, v14, v15 offset0:14 offset1:15
	s_waitcnt lgkmcnt(0)
	s_barrier
	ds_read2st64_b32 v[2:3], v27 offset1:16
	v_or_b32_e32 v4, s21, v17
	s_ashr_i32 s21, s20, 31
	v_lshl_add_u64 v[0:1], s[20:21], 1, v[24:25]
	v_add_u32_e32 v28, s40, v19
	s_waitcnt lgkmcnt(0)
	v_add_f32_e32 v2, 0, v2
	v_add_f32_e32 v5, v2, v3
	ds_read2st64_b32 v[2:3], v27 offset0:32 offset1:48
	s_cmpk_lt_i32 s44, 0x100
	s_waitcnt lgkmcnt(0)
	v_add_f32_e32 v2, v5, v2
	v_add_f32_e32 v5, v2, v3
	ds_read2st64_b32 v[2:3], v27 offset0:64 offset1:80
	s_waitcnt lgkmcnt(0)
	v_add_f32_e32 v2, v5, v2
	v_add_f32_e32 v5, v2, v3
	ds_read2st64_b32 v[2:3], v27 offset0:96 offset1:112
	s_waitcnt lgkmcnt(0)
	v_add_f32_e32 v2, v5, v2
	v_add_f32_e32 v3, v2, v3
	v_add_u32_e32 v2, s1, v4
	v_cvt_pk_bf16_f32 v5, v3, s0
	v_ashrrev_i32_e32 v3, 31, v2
	v_lshlrev_b64 v[2:3], 11, v[2:3]
	v_lshl_add_u64 v[2:3], v[0:1], 0, v[2:3]
	global_store_short v[2:3], v5, off
	ds_read2st64_b32 v[2:3], v28 offset1:16
	s_waitcnt lgkmcnt(0)
	v_add_f32_e32 v2, 0, v2
	v_add_f32_e32 v5, v2, v3
	ds_read2st64_b32 v[2:3], v28 offset0:32 offset1:48
	s_waitcnt lgkmcnt(0)
	v_add_f32_e32 v2, v5, v2
	v_add_f32_e32 v5, v2, v3
	ds_read2st64_b32 v[2:3], v28 offset0:64 offset1:80
	s_waitcnt lgkmcnt(0)
	v_add_f32_e32 v2, v5, v2
	v_add_f32_e32 v5, v2, v3
	ds_read2st64_b32 v[2:3], v28 offset0:96 offset1:112
	s_waitcnt lgkmcnt(0)
	v_add_f32_e32 v2, v5, v2
	v_add_f32_e32 v3, v2, v3
	v_add_u32_e32 v2, s12, v4
	v_cvt_pk_bf16_f32 v4, v3, s0
	v_ashrrev_i32_e32 v3, 31, v2
	v_lshlrev_b64 v[2:3], 11, v[2:3]
	v_lshl_add_u64 v[0:1], v[0:1], 0, v[2:3]
	global_store_short v[0:1], v4, off
	s_barrier
	s_cbranch_scc1 .LBB0_101
	s_add_u32 s20, s54, s8
	s_addc_u32 s21, s55, s9
	s_add_u32 s8, s2, s8
	v_lshlrev_b32_e32 v132, 1, v18
	s_addc_u32 s9, s3, s9
	v_lshl_add_u64 v[0:1], s[20:21], 0, v[132:133]
	s_mov_b64 s[20:21], 0x3f4c4000
	v_lshl_add_u64 v[20:21], s[8:9], 0, v[132:133]
	v_lshlrev_b32_e32 v132, 1, v16
	v_lshl_add_u64 v[18:19], v[0:1], 0, s[20:21]
	v_lshl_add_u64 v[0:1], s[54:55], 0, v[132:133]
	s_mov_b64 s[8:9], 0x39e20000
	v_lshl_add_u64 v[22:23], v[0:1], 0, s[8:9]

; #define MFMA32T(a, b, c) __builtin_amdgcn_mfma_f32_32x32x16_bf16((a), (b), (c), 0, 0, 0)
; __device__ __forceinline__ int crow32(int i, int hh) { return (i & 3) + 8 * (i >> 2) + 4 * hh; }
;     ...
;     for (int t = b0; t < mt * nt; t += G) { const int mb = t / nt, nb = t % nt;
;         const bf16_t* ap = A + (size_t)(mb * 32 + r) * lda + wave * 16 + 8 * hh; const int brow = f.brow(nb);
;         const bf16_t* bp = Bt + (size_t)(brow + r) * ldb + wave * 16 + 8 * hh; const bf16_t* bp2 = DUAL ? Bt2 + (size_t)(brow + r) * ldb + wave * 16 + 8 * hh : bp;
;         f32x16 acc, acc2;
; #pragma unroll
;         for (int i = 0; i < 16; ++i) { acc[i] = 0.f; acc2[i] = 0.f; }
; #pragma unroll 8
;         for (int k = 0; k < K; k += 128) { const bf16x8 av = *(const bf16x8*)(ap + k); acc = MFMA32T(av, *(const bf16x8*)(bp + k), acc); if (DUAL) acc2 = MFMA32T(av, *(const bf16x8*)(bp2 + k), acc2); }
; #pragma unroll
;         for (int i = 0; i < 16; ++i) { red[(wave * 16 + i) * 64 + lane] = acc[i]; if (DUAL) red[8192 + (wave * 16 + i) * 64 + lane] = acc2[i]; }
;         __syncthreads();
; #pragma unroll
;         for (int ii = 0; ii < 2; ++ii) { const int i = 2 * wave + ii; float v = 0.f, v2 = 0.f;
; #pragma unroll
;             for (int w = 0; w < 8; ++w) { v += red[(w * 16 + i) * 64 + lane]; if (DUAL) v2 += red[8192 + (w * 16 + i) * 64 + lane]; }
;             f(v, v2, mb * 32 + crow32(i, hh), nb * 32, r); }
.LBB0_444:
	s_mul_hi_i32 s2, s12, 0x5397829d
	s_lshr_b32 s3, s2, 31
	s_ashr_i32 s2, s2, 4
	s_add_i32 s2, s2, s3
	s_mul_i32 s3, s2, 0xffffffcf
	s_lshl_b32 s4, s2, 5
	s_mulk_i32 s2, 0xf9e0
	v_or_b32_e32 v0, s4, v32
	s_add_i32 s10, s33, s2
	v_ashrrev_i32_e32 v1, 31, v0
	v_add_u32_e32 v2, s10, v22
	v_lshlrev_b64 v[0:1], 11, v[0:1]
	v_ashrrev_i32_e32 v3, 31, v2
	v_lshlrev_b64 v[2:3], 11, v[2:3]
	v_lshl_add_u64 v[34:35], v[16:17], 0, v[0:1]
	v_lshl_add_u64 v[36:37], v[18:19], 0, v[2:3]
	global_load_dwordx4 v[0:3], v[34:35], off
	global_load_dwordx4 v[4:7], v[36:37], off
	global_load_dwordx4 v[24:27], v[34:35], off offset:256
	global_load_dwordx4 v[28:31], v[36:37], off offset:256
	v_add_u32_e32 v23, s0, v20
	s_add_i32 s3, s12, s3
	s_cmp_gt_i32 s3, 15
	s_mov_b64 s[34:35], -1
	s_waitcnt vmcnt(0)
	v_mfma_f32_32x32x16_bf16 v[0:15], v[0:3], v[4:7], 0
	s_waitcnt vmcnt(0)
	v_mfma_f32_32x32x16_bf16 v[0:15], v[24:27], v[28:31], v[0:15]
	global_load_dwordx4 v[24:27], v[34:35], off offset:512
	global_load_dwordx4 v[28:31], v[36:37], off offset:512
	global_load_dwordx4 v[200:203], v[34:35], off offset:768
	global_load_dwordx4 v[204:207], v[36:37], off offset:768
	global_load_dwordx4 v[212:215], v[34:35], off offset:1024
	global_load_dwordx4 v[216:219], v[36:37], off offset:1024
	global_load_dwordx4 v[224:227], v[34:35], off offset:1280
	global_load_dwordx4 v[228:231], v[36:37], off offset:1280
	s_waitcnt vmcnt(6)
	v_mfma_f32_32x32x16_bf16 v[0:15], v[24:27], v[28:31], v[0:15]
	global_load_dwordx4 v[24:27], v[34:35], off offset:1536
	global_load_dwordx4 v[28:31], v[36:37], off offset:1536
	s_waitcnt vmcnt(6)
	v_mfma_f32_32x32x16_bf16 v[0:15], v[200:203], v[204:207], v[0:15]
	global_load_dwordx4 v[200:203], v[34:35], off offset:1792
	global_load_dwordx4 v[204:207], v[36:37], off offset:1792
	s_waitcnt vmcnt(6)
	v_mfma_f32_32x32x16_bf16 v[0:15], v[212:215], v[216:219], v[0:15]
	s_waitcnt vmcnt(4)
	v_mfma_f32_32x32x16_bf16 v[0:15], v[224:227], v[228:231], v[0:15]
	s_waitcnt vmcnt(2)
	v_mfma_f32_32x32x16_bf16 v[0:15], v[24:27], v[28:31], v[0:15]
	s_waitcnt vmcnt(0)
	v_mfma_f32_32x32x16_bf16 v[0:15], v[200:203], v[204:207], v[0:15]
	s_nop 11
	ds_write2st64_b32 v23, v0, v1 offset1:1
	ds_write2st64_b32 v23, v2, v3 offset0:2 offset1:3
	ds_write2st64_b32 v23, v4, v5 offset0:4 offset1:5
	ds_write2st64_b32 v23, v6, v7 offset0:6 offset1:7
	ds_write2st64_b32 v23, v8, v9 offset0:8 offset1:9
	ds_write2st64_b32 v23, v10, v11 offset0:10 offset1:11
	ds_write2st64_b32 v23, v12, v13 offset0:12 offset1:13
	ds_write2st64_b32 v23, v14, v15 offset0:14 offset1:15
	v_add_u32_e32 v3, s1, v20
	s_waitcnt lgkmcnt(0)
	s_barrier
	ds_read2st64_b32 v[0:1], v3 offset1:16
	v_or_b32_e32 v2, s4, v21
	s_cselect_b64 s[4:5], -1, 0
	s_cmp_gt_u32 s3, 39
	s_cselect_b64 s[2:3], -1, 0
	s_waitcnt lgkmcnt(0)
	v_add_f32_e32 v0, 0, v0
	v_add_f32_e32 v4, v0, v1
	ds_read2st64_b32 v[0:1], v3 offset0:32 offset1:48
	s_waitcnt lgkmcnt(0)
	v_add_f32_e32 v0, v4, v0
	v_add_f32_e32 v4, v0, v1
	ds_read2st64_b32 v[0:1], v3 offset0:64 offset1:80
	s_waitcnt lgkmcnt(0)
	v_add_f32_e32 v0, v4, v0
	v_add_f32_e32 v4, v0, v1
	ds_read2st64_b32 v[0:1], v3 offset0:96 offset1:112
	s_waitcnt lgkmcnt(0)
	v_add_f32_e32 v0, v4, v0
	v_add_f32_e32 v3, v0, v1
	v_add_u32_e32 v0, s23, v2
	v_ashrrev_i32_e32 v1, 31, v0
	v_lshl_add_u64 v[4:5], v[0:1], 2, s[18:19]
	global_load_dword v4, v[4:5], off
	s_waitcnt vmcnt(0)
	v_fmamk_f32 v4, v4, 0x3a800000, v134
	v_cmp_gt_f32_e32 vcc, s13, v4
	v_mul_f32_e32 v5, 0x4b800000, v4
	s_nop 0
	v_cndmask_b32_e32 v4, v4, v5, vcc
	v_rsq_f32_e32 v4, v4
	s_nop 0
	v_mul_f32_e32 v5, 0x45800000, v4
	v_cndmask_b32_e32 v4, v4, v5, vcc
	v_mul_f32_e32 v3, v3, v4
	v_cvt_pk_bf16_f32 v3, v3, s0
	s_and_b64 vcc, exec, s[4:5]
	s_cbranch_vccz .LBB0_452
	s_mov_b64 s[20:21], -1
	s_and_b64 vcc, exec, s[2:3]
	s_cbranch_vccz .LBB0_447
	v_mov_b64_e32 v[4:5], s[16:17]
	v_mad_i64_i32 v[4:5], s[20:21], v0, s79, v[4:5]
	v_lshl_add_u64 v[4:5], s[10:11], 1, v[4:5]
	v_lshlrev_b32_e32 v132, 1, v32
	v_lshl_add_u64 v[4:5], v[4:5], 0, v[132:133]
	global_store_short v[4:5], v3, off offset:-2560
	s_mov_b64 s[20:21], 0

; #define MFMA32T(a, b, c) __builtin_amdgcn_mfma_f32_32x32x16_bf16((a), (b), (c), 0, 0, 0)
; __device__ __forceinline__ int crow32(int i, int hh) { return (i & 3) + 8 * (i >> 2) + 4 * hh; }
;     ...
;     for (int t = b0; t < mt * nt; t += G) { const int mb = t / nt, nb = t % nt;
;         const bf16_t* ap = A + (size_t)(mb * 32 + r) * lda + wave * 16 + 8 * hh; const int brow = f.brow(nb);
;         const bf16_t* bp = Bt + (size_t)(brow + r) * ldb + wave * 16 + 8 * hh; const bf16_t* bp2 = DUAL ? Bt2 + (size_t)(brow + r) * ldb + wave * 16 + 8 * hh : bp;
;         f32x16 acc, acc2;
; #pragma unroll
;         for (int i = 0; i < 16; ++i) { acc[i] = 0.f; acc2[i] = 0.f; }
; #pragma unroll 8
;         for (int k = 0; k < K; k += 128) { const bf16x8 av = *(const bf16x8*)(ap + k); acc = MFMA32T(av, *(const bf16x8*)(bp + k), acc); if (DUAL) acc2 = MFMA32T(av, *(const bf16x8*)(bp2 + k), acc2); }
; #pragma unroll
;         for (int i = 0; i < 16; ++i) { red[(wave * 16 + i) * 64 + lane] = acc[i]; if (DUAL) red[8192 + (wave * 16 + i) * 64 + lane] = acc2[i]; }
;         __syncthreads();
; #pragma unroll
;         for (int ii = 0; ii < 2; ++ii) { const int i = 2 * wave + ii; float v = 0.f, v2 = 0.f;
; #pragma unroll
;             for (int w = 0; w < 8; ++w) { v += red[(w * 16 + i) * 64 + lane]; if (DUAL) v2 += red[8192 + (w * 16 + i) * 64 + lane]; }
;             f(v, v2, mb * 32 + crow32(i, hh), nb * 32, r); }
.LBB0_661:
	s_ashr_i32 s2, s0, 31
	s_lshr_b32 s2, s2, 27
	s_add_i32 s2, s0, s2
	s_and_b32 s3, s2, 0xffffffe0
	s_lshl_b32 s2, s2, 5
	s_and_b32 s2, s2, 0xfffffc00
	v_or_b32_e32 v0, s3, v16
	s_sub_i32 s2, s10, s2
	v_ashrrev_i32_e32 v1, 31, v0
	v_add_u32_e32 v2, s2, v16
	v_lshlrev_b64 v[0:1], 11, v[0:1]
	v_ashrrev_i32_e32 v3, 31, v2
	v_lshlrev_b64 v[2:3], 11, v[2:3]
	v_lshl_add_u64 v[32:33], v[18:19], 0, v[0:1]
	v_lshl_add_u64 v[34:35], v[20:21], 0, v[2:3]
	global_load_dwordx4 v[0:3], v[32:33], off
	global_load_dwordx4 v[4:7], v[34:35], off
	global_load_dwordx4 v[24:27], v[32:33], off offset:256
	global_load_dwordx4 v[28:31], v[34:35], off offset:256
	v_add_u32_e32 v23, s1, v17
	s_andn2_b64 vcc, exec, s[4:5]
	s_waitcnt vmcnt(0)
	v_mfma_f32_32x32x16_bf16 v[0:15], v[0:3], v[4:7], 0
	s_waitcnt vmcnt(0)
	v_mfma_f32_32x32x16_bf16 v[0:15], v[24:27], v[28:31], v[0:15]
	global_load_dwordx4 v[24:27], v[32:33], off offset:512
	global_load_dwordx4 v[28:31], v[34:35], off offset:512
	global_load_dwordx4 v[200:203], v[32:33], off offset:768
	global_load_dwordx4 v[204:207], v[34:35], off offset:768
	global_load_dwordx4 v[212:215], v[32:33], off offset:1024
	global_load_dwordx4 v[216:219], v[34:35], off offset:1024
	global_load_dwordx4 v[224:227], v[32:33], off offset:1280
	global_load_dwordx4 v[228:231], v[34:35], off offset:1280
	s_waitcnt vmcnt(6)
	v_mfma_f32_32x32x16_bf16 v[0:15], v[24:27], v[28:31], v[0:15]
	global_load_dwordx4 v[24:27], v[32:33], off offset:1536
	global_load_dwordx4 v[28:31], v[34:35], off offset:1536
	s_waitcnt vmcnt(6)
	v_mfma_f32_32x32x16_bf16 v[0:15], v[200:203], v[204:207], v[0:15]
	global_load_dwordx4 v[200:203], v[32:33], off offset:1792
	global_load_dwordx4 v[204:207], v[34:35], off offset:1792
	s_waitcnt vmcnt(6)
	v_mfma_f32_32x32x16_bf16 v[0:15], v[212:215], v[216:219], v[0:15]
	s_waitcnt vmcnt(4)
	v_mfma_f32_32x32x16_bf16 v[0:15], v[224:227], v[228:231], v[0:15]
	s_waitcnt vmcnt(2)
	v_mfma_f32_32x32x16_bf16 v[0:15], v[24:27], v[28:31], v[0:15]
	s_waitcnt vmcnt(0)
	v_mfma_f32_32x32x16_bf16 v[0:15], v[200:203], v[204:207], v[0:15]
	s_nop 11
	ds_write2st64_b32 v23, v0, v1 offset1:1
	ds_write2st64_b32 v23, v2, v3 offset0:2 offset1:3
	ds_write2st64_b32 v23, v4, v5 offset0:4 offset1:5
	ds_write2st64_b32 v23, v6, v7 offset0:6 offset1:7
	ds_write2st64_b32 v23, v8, v9 offset0:8 offset1:9
	ds_write2st64_b32 v23, v10, v11 offset0:10 offset1:11
	ds_write2st64_b32 v23, v12, v13 offset0:12 offset1:13
	ds_write2st64_b32 v23, v14, v15 offset0:14 offset1:15
	v_add_u32_e32 v4, s6, v17
	s_waitcnt lgkmcnt(0)
	s_barrier
	ds_read2st64_b32 v[2:3], v4 offset1:16
	v_or_b32_e32 v6, s3, v22
	s_ashr_i32 s3, s2, 31
	v_mov_b32_e32 v1, s3
	v_or_b32_e32 v0, s2, v16
	s_waitcnt lgkmcnt(0)
	v_add_f32_e32 v2, 0, v2
	v_add_f32_e32 v5, v2, v3
	ds_read2st64_b32 v[2:3], v4 offset0:32 offset1:48
	s_mov_b64 s[2:3], -1
	s_waitcnt lgkmcnt(0)
	v_add_f32_e32 v2, v5, v2
	v_add_f32_e32 v5, v2, v3
	ds_read2st64_b32 v[2:3], v4 offset0:64 offset1:80
	s_waitcnt lgkmcnt(0)
	v_add_f32_e32 v2, v5, v2
	v_add_f32_e32 v5, v2, v3
	ds_read2st64_b32 v[2:3], v4 offset0:96 offset1:112
	s_waitcnt lgkmcnt(0)
	v_add_f32_e32 v2, v5, v2
	v_add_f32_e32 v12, v2, v3
	v_add_u32_e32 v2, s8, v6
	v_ashrrev_i32_e32 v3, 31, v2
	v_lshlrev_b64 v[4:5], 10, v[2:3]
	v_lshl_add_u64 v[4:5], v[4:5], 0, v[0:1]
	v_lshlrev_b64 v[8:9], 1, v[4:5]
	v_lshl_add_u64 v[10:11], s[26:27], 0, v[8:9]
	v_lshl_add_u64 v[8:9], s[36:37], 0, v[8:9]
	global_load_ushort v7, v[10:11], off
	s_nop 0
	global_load_ushort v8, v[8:9], off
	v_mul_f32_e32 v10, 0xbfb8aa3b, v12
	v_exp_f32_e32 v10, v10
	s_waitcnt vmcnt(1)
	v_lshlrev_b32_e32 v7, 16, v7
	v_add_f32_e32 v10, 1.0, v10
	v_rcp_f32_e32 v10, v10
	s_waitcnt vmcnt(0)
	v_lshlrev_b32_e32 v8, 16, v8
	v_fmac_f32_e32 v7, v10, v8
	v_cndmask_b32_e64 v8, 0, 1, s[4:5]
	v_cmp_ne_u32_e64 s[42:43], 1, v8
	s_cbranch_vccnz .LBB0_663
	v_lshl_add_u64 v[8:9], v[4:5], 2, s[52:53]
	s_mov_b64 s[2:3], 0
	global_store_dword v[8:9], v7, off

; #define MFMA32T(a, b, c) __builtin_amdgcn_mfma_f32_32x32x16_bf16((a), (b), (c), 0, 0, 0)
; __device__ __forceinline__ int crow32(int i, int hh) { return (i & 3) + 8 * (i >> 2) + 4 * hh; }
;     ...
;     for (int t = b0; t < mt * nt; t += G) { const int mb = t / nt, nb = t % nt;
;         const bf16_t* ap = A + (size_t)(mb * 32 + r) * lda + wave * 16 + 8 * hh; const int brow = f.brow(nb);
;         const bf16_t* bp = Bt + (size_t)(brow + r) * ldb + wave * 16 + 8 * hh; const bf16_t* bp2 = DUAL ? Bt2 + (size_t)(brow + r) * ldb + wave * 16 + 8 * hh : bp;
;         f32x16 acc, acc2;
; #pragma unroll
;         for (int i = 0; i < 16; ++i) { acc[i] = 0.f; acc2[i] = 0.f; }
; #pragma unroll 8
;         for (int k = 0; k < K; k += 128) { const bf16x8 av = *(const bf16x8*)(ap + k); acc = MFMA32T(av, *(const bf16x8*)(bp + k), acc); if (DUAL) acc2 = MFMA32T(av, *(const bf16x8*)(bp2 + k), acc2); }
; #pragma unroll
;         for (int i = 0; i < 16; ++i) { red[(wave * 16 + i) * 64 + lane] = acc[i]; if (DUAL) red[8192 + (wave * 16 + i) * 64 + lane] = acc2[i]; }
;         __syncthreads();
; #pragma unroll
;         for (int ii = 0; ii < 2; ++ii) { const int i = 2 * wave + ii; float v = 0.f, v2 = 0.f;
; #pragma unroll
;             for (int w = 0; w < 8; ++w) { v += red[(w * 16 + i) * 64 + lane]; if (DUAL) v2 += red[8192 + (w * 16 + i) * 64 + lane]; }
;             f(v, v2, mb * 32 + crow32(i, hh), nb * 32, r); }
.LBB0_1021:
	s_mul_hi_i32 s2, s0, 0x2aaaaaab
	s_lshr_b32 s3, s2, 31
	s_ashr_i32 s2, s2, 2
	s_add_i32 s2, s2, s3
	s_lshl_b32 s21, s2, 5
	s_mul_i32 s3, s2, 0xfffffd00
	s_mul_i32 s2, s2, 0xffee0000
	v_or_b32_e32 v2, s21, v23
	v_add_u32_e32 v0, s2, v25
	s_add_i32 s20, s29, s3
	v_ashrrev_i32_e32 v1, 31, v0
	v_mad_i64_i32 v[36:37], s[2:3], v2, s78, v[16:17]
	v_lshl_add_u64 v[38:39], v[18:19], 0, v[0:1]
	global_load_dwordx4 v[0:3], v[36:37], off
	global_load_dwordx4 v[4:7], v[38:39], off
	global_load_dwordx4 v[28:31], v[36:37], off offset:256
	global_load_dwordx4 v[32:35], v[38:39], off offset:256
	v_add_u32_e32 v27, s1, v22
	s_mul_i32 s2, s20, 0x2aab
	s_lshr_b32 s3, s2, 31
	s_lshr_b32 s2, s2, 20
	s_add_i32 s2, s2, s3
	s_mulk_i32 s2, 0x60
	s_sub_i32 s2, s20, s2
	s_waitcnt vmcnt(0)
	v_mfma_f32_32x32x16_bf16 v[0:15], v[0:3], v[4:7], 0
	s_waitcnt vmcnt(0)
	v_mfma_f32_32x32x16_bf16 v[0:15], v[28:31], v[32:35], v[0:15]
	global_load_dwordx4 v[28:31], v[36:37], off offset:512
	global_load_dwordx4 v[32:35], v[38:39], off offset:512
	global_load_dwordx4 v[200:203], v[36:37], off offset:768
	global_load_dwordx4 v[204:207], v[38:39], off offset:768
	global_load_dwordx4 v[212:215], v[36:37], off offset:1024
	global_load_dwordx4 v[216:219], v[38:39], off offset:1024
	global_load_dwordx4 v[224:227], v[36:37], off offset:1280
	global_load_dwordx4 v[228:231], v[38:39], off offset:1280
	s_waitcnt vmcnt(6)
	v_mfma_f32_32x32x16_bf16 v[0:15], v[28:31], v[32:35], v[0:15]
	s_waitcnt vmcnt(4)
	v_mfma_f32_32x32x16_bf16 v[0:15], v[200:203], v[204:207], v[0:15]
	s_waitcnt vmcnt(2)
	v_mfma_f32_32x32x16_bf16 v[0:15], v[212:215], v[216:219], v[0:15]
	s_waitcnt vmcnt(0)
	v_mfma_f32_32x32x16_bf16 v[0:15], v[224:227], v[228:231], v[0:15]
	s_nop 11
	ds_write2st64_b32 v27, v0, v1 offset1:1
	ds_write2st64_b32 v27, v2, v3 offset0:2 offset1:3
	ds_write2st64_b32 v27, v4, v5 offset0:4 offset1:5
	ds_write2st64_b32 v27, v6, v7 offset0:6 offset1:7
	ds_write2st64_b32 v27, v8, v9 offset0:8 offset1:9
	ds_write2st64_b32 v27, v10, v11 offset0:10 offset1:11
	ds_write2st64_b32 v27, v12, v13 offset0:12 offset1:13
	ds_write2st64_b32 v27, v14, v15 offset0:14 offset1:15
	v_add_u32_e32 v2, s10, v22
	s_waitcnt lgkmcnt(0)
	s_barrier
	ds_read2st64_b32 v[0:1], v2 offset1:16
	v_add_u32_e32 v4, s21, v24
	s_and_b32 s21, s2, 0xffff
	s_cmp_eq_u32 s21, 64
	s_cselect_b64 s[2:3], -1, 0
	s_waitcnt lgkmcnt(0)
	v_add_f32_e32 v0, 0, v0
	v_add_f32_e32 v3, v0, v1
	ds_read2st64_b32 v[0:1], v2 offset0:32 offset1:48
	s_cmp_lg_u32 s21, 64
	s_waitcnt lgkmcnt(0)
	v_add_f32_e32 v0, v3, v0
	v_add_f32_e32 v3, v0, v1
	ds_read2st64_b32 v[0:1], v2 offset0:64 offset1:80
	s_waitcnt lgkmcnt(0)
	v_add_f32_e32 v0, v3, v0
	v_add_f32_e32 v3, v0, v1
	ds_read2st64_b32 v[0:1], v2 offset0:96 offset1:112
	v_add_u32_e32 v2, s12, v4
	s_waitcnt lgkmcnt(0)
	v_add_f32_e32 v0, v3, v0
	v_add_f32_e32 v3, v0, v1
	s_cbranch_scc1 .LBB0_1023
	s_mov_b32 s21, 0x10000
	v_and_b32_e32 v0, 0x7fe, v2
	v_and_or_b32 v1, v2, 30, v183
	v_cmp_gt_i32_e32 vcc, s21, v2
	s_nop 1
	v_cndmask_b32_e32 v0, v1, v0, vcc
	v_lshl_or_b32 v0, v0, 7, v26
	global_load_dwordx2 v[0:1], v0, s[4:5]
	v_cmp_lt_i32_e32 vcc, v179, v174
	s_nop 1
	v_cndmask_b32_e32 v5, v173, v179, vcc
	v_lshlrev_b32_e32 v5, 2, v5
	ds_bpermute_b32 v5, v5, v3
	s_waitcnt vmcnt(0) lgkmcnt(0)
	v_mul_f32_e32 v1, v1, v5
	v_cndmask_b32_e64 v1, v1, -v1, s[40:41]
	v_fmac_f32_e32 v1, v3, v0
	v_mov_b32_e32 v3, v1
